# DSA selection final pass: wave masks combined on the SALU instead of re-derived through 0/1 VGPR selects (ballot trim) in 11 of 16 steps
# speedup vs baseline: 1.0094x; 1.0094x over previous
.LBB0_2464:
	v_cmp_eq_u32_e32 vcc, v14, v0
	v_cmp_gt_u32_e64 s[6:7], s56, v198
	v_cmp_gt_u32_e64 s[90:91], v14, v0
	s_and_b64 vcc, vcc, s[6:7]
	s_nop 1
	v_mbcnt_lo_u32_b32 v3, vcc_lo, 0
	v_mbcnt_hi_u32_b32 v2, vcc_hi, v3
	v_add_u32_e32 v2, s41, v2
	v_cmp_gt_u32_e64 s[8:9], s58, v2
	s_and_b64 s[8:9], vcc, s[8:9]
	s_or_b64 s[6:7], s[90:91], s[8:9]
	s_nop 1
	v_mbcnt_lo_u32_b32 v3, s6, 0
	v_mbcnt_hi_u32_b32 v2, s7, v3
	v_add_u32_e32 v2, s40, v2
	v_cmp_gt_u32_e64 s[10:11], s48, v2
	s_and_b64 s[10:11], s[6:7], s[10:11]
	s_and_saveexec_b64 s[8:9], s[10:11]
	s_cbranch_execz .LBB0_2466
	ds_read_b32 v3, v190 offset:5376
	v_lshl_add_u32 v2, v2, 2, s43
	s_waitcnt lgkmcnt(0)
	ds_write_b32 v2, v3

.LBB0_2468:
	v_cmp_eq_u32_e32 vcc, v12, v0
	v_cmp_gt_u32_e64 s[6:7], s56, v200
	v_cmp_gt_u32_e64 s[90:91], v12, v0
	s_and_b64 vcc, vcc, s[6:7]
	s_nop 1
	v_mbcnt_lo_u32_b32 v3, vcc_lo, 0
	v_mbcnt_hi_u32_b32 v2, vcc_hi, v3
	v_add_u32_e32 v2, s41, v2
	v_cmp_gt_u32_e64 s[8:9], s58, v2
	s_and_b64 s[8:9], vcc, s[8:9]
	s_or_b64 s[6:7], s[90:91], s[8:9]
	s_nop 1
	v_mbcnt_lo_u32_b32 v3, s6, 0
	v_mbcnt_hi_u32_b32 v2, s7, v3
	v_add_u32_e32 v2, s40, v2
	v_cmp_gt_u32_e64 s[10:11], s48, v2
	s_and_b64 s[10:11], s[6:7], s[10:11]
	s_and_saveexec_b64 s[8:9], s[10:11]
	s_cbranch_execz .LBB0_2470
	ds_read_b32 v3, v190 offset:5888
	v_lshl_add_u32 v2, v2, 2, s43
	s_waitcnt lgkmcnt(0)
	ds_write_b32 v2, v3

.LBB0_2472:
	v_cmp_eq_u32_e32 vcc, v10, v0
	v_cmp_gt_u32_e64 s[6:7], s56, v202
	v_cmp_gt_u32_e64 s[90:91], v10, v0
	s_and_b64 vcc, vcc, s[6:7]
	s_nop 1
	v_mbcnt_lo_u32_b32 v3, vcc_lo, 0
	v_mbcnt_hi_u32_b32 v2, vcc_hi, v3
	v_add_u32_e32 v2, s41, v2
	v_cmp_gt_u32_e64 s[8:9], s58, v2
	s_and_b64 s[8:9], vcc, s[8:9]
	s_or_b64 s[6:7], s[90:91], s[8:9]
	s_nop 1
	v_mbcnt_lo_u32_b32 v3, s6, 0
	v_mbcnt_hi_u32_b32 v2, s7, v3
	v_add_u32_e32 v2, s40, v2
	v_cmp_gt_u32_e64 s[10:11], s48, v2
	s_and_b64 s[10:11], s[6:7], s[10:11]
	s_and_saveexec_b64 s[8:9], s[10:11]
	s_cbranch_execz .LBB0_2474
	ds_read_b32 v3, v190 offset:6400
	v_lshl_add_u32 v2, v2, 2, s43
	s_waitcnt lgkmcnt(0)
	ds_write_b32 v2, v3

.LBB0_2476:
	v_cmp_eq_u32_e32 vcc, v8, v0
	v_cmp_gt_u32_e64 s[6:7], s56, v204
	v_cmp_gt_u32_e64 s[90:91], v8, v0
	s_and_b64 vcc, vcc, s[6:7]
	s_nop 1
	v_mbcnt_lo_u32_b32 v3, vcc_lo, 0
	v_mbcnt_hi_u32_b32 v2, vcc_hi, v3
	v_add_u32_e32 v2, s41, v2
	v_cmp_gt_u32_e64 s[8:9], s58, v2
	s_and_b64 s[8:9], vcc, s[8:9]
	s_or_b64 s[6:7], s[90:91], s[8:9]
	s_nop 1
	v_mbcnt_lo_u32_b32 v3, s6, 0
	v_mbcnt_hi_u32_b32 v2, s7, v3
	v_add_u32_e32 v2, s40, v2
	v_cmp_gt_u32_e64 s[10:11], s48, v2
	s_and_b64 s[10:11], s[6:7], s[10:11]
	s_and_saveexec_b64 s[8:9], s[10:11]
	s_cbranch_execz .LBB0_2478
	ds_read_b32 v3, v190 offset:6912
	v_lshl_add_u32 v2, v2, 2, s43
	s_waitcnt lgkmcnt(0)
	ds_write_b32 v2, v3

.LBB0_2480:
	v_cmp_eq_u32_e32 vcc, v6, v0
	v_cmp_gt_u32_e64 s[6:7], s56, v206
	v_cmp_gt_u32_e64 s[90:91], v6, v0
	s_and_b64 vcc, vcc, s[6:7]
	s_nop 1
	v_mbcnt_lo_u32_b32 v3, vcc_lo, 0
	v_mbcnt_hi_u32_b32 v2, vcc_hi, v3
	v_add_u32_e32 v2, s41, v2
	v_cmp_gt_u32_e64 s[8:9], s58, v2
	s_and_b64 s[8:9], vcc, s[8:9]
	s_or_b64 s[6:7], s[90:91], s[8:9]
	s_nop 1
	v_mbcnt_lo_u32_b32 v3, s6, 0
	v_mbcnt_hi_u32_b32 v2, s7, v3
	v_add_u32_e32 v2, s40, v2
	v_cmp_gt_u32_e64 s[10:11], s48, v2
	s_and_b64 s[10:11], s[6:7], s[10:11]
	s_and_saveexec_b64 s[8:9], s[10:11]
	s_cbranch_execz .LBB0_2482
	ds_read_b32 v3, v190 offset:7424
	v_lshl_add_u32 v2, v2, 2, s43
	s_waitcnt lgkmcnt(0)
	ds_write_b32 v2, v3

.LBB0_2604:
	v_cmp_eq_u32_e32 vcc, v15, v0
	v_cmp_gt_u32_e64 s[6:7], s56, v197
	v_cmp_gt_u32_e64 s[90:91], v15, v0
	s_and_b64 vcc, vcc, s[6:7]
	s_nop 1
	v_mbcnt_lo_u32_b32 v3, vcc_lo, 0
	v_mbcnt_hi_u32_b32 v2, vcc_hi, v3
	v_add_u32_e32 v2, s41, v2
	v_cmp_gt_u32_e64 s[8:9], s58, v2
	s_and_b64 s[8:9], vcc, s[8:9]
	s_or_b64 s[6:7], s[90:91], s[8:9]
	s_nop 1
	v_mbcnt_lo_u32_b32 v3, s6, 0
	v_mbcnt_hi_u32_b32 v2, s7, v3
	v_add_u32_e32 v2, s40, v2
	v_cmp_gt_u32_e64 s[10:11], s48, v2
	s_and_b64 s[10:11], s[6:7], s[10:11]
	s_and_saveexec_b64 s[8:9], s[10:11]
	s_cbranch_execz .LBB0_2606
	ds_read_b32 v3, v190 offset:5120
	v_lshl_add_u32 v2, v2, 2, s43
	s_waitcnt lgkmcnt(0)
	ds_write_b32 v2, v3

.LBB0_2608:
	v_cmp_eq_u32_e32 vcc, v13, v0
	v_cmp_gt_u32_e64 s[6:7], s56, v199
	v_cmp_gt_u32_e64 s[90:91], v13, v0
	s_and_b64 vcc, vcc, s[6:7]
	s_nop 1
	v_mbcnt_lo_u32_b32 v3, vcc_lo, 0
	v_mbcnt_hi_u32_b32 v2, vcc_hi, v3
	v_add_u32_e32 v2, s41, v2
	v_cmp_gt_u32_e64 s[8:9], s58, v2
	s_and_b64 s[8:9], vcc, s[8:9]
	s_or_b64 s[6:7], s[90:91], s[8:9]
	s_nop 1
	v_mbcnt_lo_u32_b32 v3, s6, 0
	v_mbcnt_hi_u32_b32 v2, s7, v3
	v_add_u32_e32 v2, s40, v2
	v_cmp_gt_u32_e64 s[10:11], s48, v2
	s_and_b64 s[10:11], s[6:7], s[10:11]
	s_and_saveexec_b64 s[8:9], s[10:11]
	s_cbranch_execz .LBB0_2610
	ds_read_b32 v3, v190 offset:5632
	v_lshl_add_u32 v2, v2, 2, s43
	s_waitcnt lgkmcnt(0)
	ds_write_b32 v2, v3

.LBB0_2612:
	v_cmp_eq_u32_e32 vcc, v11, v0
	v_cmp_gt_u32_e64 s[6:7], s56, v201
	v_cmp_gt_u32_e64 s[90:91], v11, v0
	s_and_b64 vcc, vcc, s[6:7]
	s_nop 1
	v_mbcnt_lo_u32_b32 v3, vcc_lo, 0
	v_mbcnt_hi_u32_b32 v2, vcc_hi, v3
	v_add_u32_e32 v2, s41, v2
	v_cmp_gt_u32_e64 s[8:9], s58, v2
	s_and_b64 s[8:9], vcc, s[8:9]
	s_or_b64 s[6:7], s[90:91], s[8:9]
	s_nop 1
	v_mbcnt_lo_u32_b32 v3, s6, 0
	v_mbcnt_hi_u32_b32 v2, s7, v3
	v_add_u32_e32 v2, s40, v2
	v_cmp_gt_u32_e64 s[10:11], s48, v2
	s_and_b64 s[10:11], s[6:7], s[10:11]
	s_and_saveexec_b64 s[8:9], s[10:11]
	s_cbranch_execz .LBB0_2614
	ds_read_b32 v3, v190 offset:6144
	v_lshl_add_u32 v2, v2, 2, s43
	s_waitcnt lgkmcnt(0)
	ds_write_b32 v2, v3

.LBB0_2616:
	v_cmp_eq_u32_e32 vcc, v9, v0
	v_cmp_gt_u32_e64 s[6:7], s56, v203
	v_cmp_gt_u32_e64 s[90:91], v9, v0
	s_and_b64 vcc, vcc, s[6:7]
	s_nop 1
	v_mbcnt_lo_u32_b32 v3, vcc_lo, 0
	v_mbcnt_hi_u32_b32 v2, vcc_hi, v3
	v_add_u32_e32 v2, s41, v2
	v_cmp_gt_u32_e64 s[8:9], s58, v2
	s_and_b64 s[8:9], vcc, s[8:9]
	s_or_b64 s[6:7], s[90:91], s[8:9]
	s_nop 1
	v_mbcnt_lo_u32_b32 v3, s6, 0
	v_mbcnt_hi_u32_b32 v2, s7, v3
	v_add_u32_e32 v2, s40, v2
	v_cmp_gt_u32_e64 s[10:11], s48, v2
	s_and_b64 s[10:11], s[6:7], s[10:11]
	s_and_saveexec_b64 s[8:9], s[10:11]
	s_cbranch_execz .LBB0_2618
	ds_read_b32 v3, v190 offset:6656
	v_lshl_add_u32 v2, v2, 2, s43
	s_waitcnt lgkmcnt(0)
	ds_write_b32 v2, v3

.LBB0_2620:
	v_cmp_eq_u32_e32 vcc, v7, v0
	v_cmp_gt_u32_e64 s[6:7], s56, v205
	v_cmp_gt_u32_e64 s[90:91], v7, v0
	s_and_b64 vcc, vcc, s[6:7]
	s_nop 1
	v_mbcnt_lo_u32_b32 v3, vcc_lo, 0
	v_mbcnt_hi_u32_b32 v2, vcc_hi, v3
	v_add_u32_e32 v2, s41, v2
	v_cmp_gt_u32_e64 s[8:9], s58, v2
	s_and_b64 s[8:9], vcc, s[8:9]
	s_or_b64 s[6:7], s[90:91], s[8:9]
	s_nop 1
	v_mbcnt_lo_u32_b32 v3, s6, 0
	v_mbcnt_hi_u32_b32 v2, s7, v3
	v_add_u32_e32 v2, s40, v2
	v_cmp_gt_u32_e64 s[10:11], s48, v2
	s_and_b64 s[10:11], s[6:7], s[10:11]
	s_and_saveexec_b64 s[8:9], s[10:11]
	s_cbranch_execz .LBB0_2622
	ds_read_b32 v3, v190 offset:7168
	v_lshl_add_u32 v2, v2, 2, s43
	s_waitcnt lgkmcnt(0)
	ds_write_b32 v2, v3

.LBB0_2624:
	v_cmp_eq_u32_e32 vcc, v5, v0
	v_cmp_gt_u32_e64 s[6:7], s56, v207
	v_cmp_gt_u32_e64 s[90:91], v5, v0
	s_and_b64 vcc, vcc, s[6:7]
	s_nop 1
	v_mbcnt_lo_u32_b32 v3, vcc_lo, 0
	v_mbcnt_hi_u32_b32 v2, vcc_hi, v3
	v_add_u32_e32 v2, s41, v2
	v_cmp_gt_u32_e64 s[8:9], s58, v2
	s_and_b64 s[8:9], vcc, s[8:9]
	s_or_b64 s[6:7], s[90:91], s[8:9]
	s_nop 1
	v_mbcnt_lo_u32_b32 v3, s6, 0
	v_mbcnt_hi_u32_b32 v2, s7, v3
	v_add_u32_e32 v2, s40, v2
	v_cmp_gt_u32_e64 s[10:11], s48, v2
	s_and_b64 s[10:11], s[6:7], s[10:11]
	s_and_saveexec_b64 s[8:9], s[10:11]
	s_cbranch_execz .LBB0_2626
	ds_read_b32 v3, v190 offset:7680
	v_lshl_add_u32 v2, v2, 2, s43
	s_waitcnt lgkmcnt(0)
	ds_write_b32 v2, v3
